# q_up epilogue: cos/sin loads issued four blocks ahead into spare registers (was one L2 round trip per block), on top of previous best
# baseline (speedup 1.0000x reference)
.LBB0_427:
	s_lshl_b32 s0, s66, 8
	s_add_i32 s4, s0, s44
	v_or_b32_e32 v108, s4, v199
	v_mov_b64_e32 v[104:105], s[16:17]
	v_mad_i64_i32 v[106:107], s[0:1], v108, s56, v[104:105]
	global_load_dwordx4 v[180:183], v[106:107], off
	global_load_dwordx4 v[184:187], v[106:107], off offset:16
	global_load_dwordx4 v[188:191], v[106:107], off offset:32
	v_add_u32_e32 v106, 0x80, v108
	v_mad_i64_i32 v[112:113], s[0:1], v106, s56, v[104:105]
	global_load_dwordx4 v[104:107], v[112:113], off offset:32
	global_load_dwordx4 v[108:111], v[112:113], off offset:16
	s_nop 0
	global_load_dwordx4 v[112:115], v[112:113], off
	v_lshl_or_b32 v158, s65, 8, v171
	v_mul_hi_i32 v150, v158, s49
	v_lshrrev_b32_e32 v159, 31, v150
	v_lshrrev_b32_e32 v150, 5, v150
	v_add_u32_e32 v150, v150, v159
	v_or_b32_e32 v178, s4, v162
	v_lshlrev_b32_e32 v179, 5, v178
	v_mul_lo_u32 v150, v150, s59
	v_sub_u32_e32 v150, v158, v150
	v_cmp_lt_i32_e64 s[4:5], s60, v150
	v_add_u32_e32 v150, 0xffffff80, v150
	v_max_i32_e32 v232, 0, v150
	v_lshrrev_b32_e32 v232, 1, v232
	v_or_b32_e32 v234, 0x80, v158
	v_mul_hi_i32 v235, v234, s49
	v_lshrrev_b32_e32 v246, 31, v235
	v_lshrrev_b32_e32 v235, 5, v235
	v_add_u32_e32 v235, v235, v246
	v_mul_lo_u32 v235, v235, s59
	v_sub_u32_e32 v234, v234, v235
	v_add_u32_e32 v234, 0xffffff80, v234
	v_max_i32_e32 v234, 0, v234
	v_lshrrev_b32_e32 v234, 1, v234
	v_mov_b32_e32 v247, 0
	v_lshlrev_b32_e32 v235, 5, v178
	v_and_b32_e32 v235, 0xffe0, v235
	v_add_u32_e32 v246, v235, v232
	v_lshl_add_u64 v[244:245], v[246:247], 3, s[54:55]
	global_load_dwordx4 v[200:203], v[244:245], off
	global_load_dwordx4 v[204:207], v[244:245], off offset:16
	v_lshlrev_b32_e32 v235, 5, v178
	v_and_b32_e32 v235, 0xffe0, v235
	v_add_u32_e32 v246, v235, v234
	v_lshl_add_u64 v[244:245], v[246:247], 3, s[54:55]
	global_load_dwordx4 v[208:211], v[244:245], off
	global_load_dwordx4 v[212:215], v[244:245], off offset:16
	v_add_u32_e32 v235, 0x10, v178
	v_lshlrev_b32_e32 v235, 5, v235
	v_and_b32_e32 v235, 0xffe0, v235
	v_add_u32_e32 v246, v235, v232
	v_lshl_add_u64 v[244:245], v[246:247], 3, s[54:55]
	global_load_dwordx4 v[216:219], v[244:245], off
	global_load_dwordx4 v[220:223], v[244:245], off offset:16
	v_add_u32_e32 v235, 0x10, v178
	v_lshlrev_b32_e32 v235, 5, v235
	v_and_b32_e32 v235, 0xffe0, v235
	v_add_u32_e32 v246, v235, v234
	v_lshl_add_u64 v[244:245], v[246:247], 3, s[54:55]
	global_load_dwordx4 v[224:227], v[244:245], off
	global_load_dwordx4 v[228:231], v[244:245], off offset:16
	s_waitcnt vmcnt(8)
	v_add_f32_e32 v160, v180, v181
	v_add_f32_e32 v180, v182, v183
	v_add_f32_e32 v182, v184, v185
	v_add_f32_e32 v184, v186, v187
	v_mov_b32_e32 v161, v188
	v_mov_b32_e32 v181, v189
	v_mov_b32_e32 v183, v190
	v_mov_b32_e32 v185, v191
	v_pk_add_f32 v[160:161], v[160:161], v[180:181]
	v_pk_add_f32 v[180:181], v[182:183], v[184:185]
	s_nop 0
	v_pk_add_f32 v[160:161], v[160:161], v[180:181]
	s_nop 0
	v_add_f32_e32 v160, v160, v161
	v_fmamk_f32 v160, v160, 0x3b2aaaab, v175
	v_mul_f32_e32 v161, 0x4f800000, v160
	v_cmp_gt_f32_e32 vcc, s57, v160
	s_nop 1
	v_cndmask_b32_e32 v160, v160, v161, vcc
	v_sqrt_f32_e32 v161, v160
	s_nop 0
	v_add_u32_e32 v159, -1, v161
	v_add_u32_e32 v180, 1, v161
	v_fma_f32 v181, -v159, v161, v160
	v_fma_f32 v182, -v180, v161, v160
	v_cmp_ge_f32_e64 s[0:1], 0, v181
	v_and_b32_e32 v181, 0xf9e0, v179
	s_nop 0
	v_cndmask_b32_e64 v159, v161, v159, s[0:1]
	v_cmp_lt_f32_e64 s[0:1], 0, v182
	s_nop 1
	v_cndmask_b32_e64 v159, v159, v180, s[0:1]
	v_mul_f32_e32 v161, 0x37800000, v159
	v_cndmask_b32_e32 v159, v159, v161, vcc
	v_cmp_class_f32_e32 vcc, v160, v176
	s_nop 1
	v_cndmask_b32_e32 v159, v159, v160, vcc
	v_div_scale_f32 v160, s[0:1], v159, v159, s58
	v_rcp_f32_e32 v161, v160
	v_div_scale_f32 v179, vcc, s58, v159, s58
	v_fma_f32 v180, -v160, v161, 1.0
	v_fmac_f32_e32 v161, v180, v161
	v_mul_f32_e32 v180, v179, v161
	v_fma_f32 v182, -v160, v180, v179
	v_fmac_f32_e32 v180, v182, v161
	v_fma_f32 v160, -v160, v180, v179
	v_div_fmas_f32 v160, v160, v161, v180
	v_div_fixup_f32 v180, v160, v159, s58
	ds_bpermute_b32 v160, v177, v180
	v_lshrrev_b32_e32 v179, 1, v150
	s_waitcnt lgkmcnt(0)
	v_pk_mul_f32 v[138:139], v[138:139], v[160:161] op_sel_hi:[1,0]
	v_pk_mul_f32 v[136:137], v[136:137], v[160:161] op_sel_hi:[1,0]
	v_pk_mul_f32 v[134:135], v[134:135], v[160:161] op_sel_hi:[1,0]
	v_pk_mul_f32 v[132:133], v[132:133], v[160:161] op_sel_hi:[1,0]
	v_add_u32_e32 v235, 0x20, v178
	v_lshlrev_b32_e32 v235, 5, v235
	v_and_b32_e32 v235, 0xffe0, v235
	v_add_u32_e32 v246, v235, v232
	v_lshl_add_u64 v[244:245], v[246:247], 3, s[54:55]
	global_load_dwordx4 v[236:239], v[244:245], off
	global_load_dwordx4 v[240:243], v[244:245], off offset:16
	s_and_saveexec_b64 s[0:1], s[4:5]
	v_readlane_b32 s68, v249, 42
	v_readlane_b32 s69, v249, 43
	s_cbranch_execz .LBB0_429
	s_waitcnt vmcnt(8)
	v_mov_b64_e32 v[182:183], v[204:205]
	v_mov_b64_e32 v[184:185], v[206:207]
	v_mov_b64_e32 v[186:187], v[200:201]
	v_mov_b64_e32 v[188:189], v[202:203]
	s_nop 0
	v_pk_mul_f32 v[194:195], v[132:133], v[182:183] op_sel:[1,1] op_sel_hi:[1,0]
	s_nop 0
	v_pk_mul_f32 v[192:193], v[136:137], v[186:187] op_sel:[1,1] op_sel_hi:[1,0]
	v_pk_mul_f32 v[190:191], v[136:137], v[186:187]
	v_pk_fma_f32 v[136:137], v[136:137], v[186:187], v[192:193] op_sel_hi:[0,1,1]
	v_mul_f32_e32 v136, v139, v189
	v_pk_fma_f32 v[186:187], v[138:139], v[188:189], v[136:137] op_sel_hi:[1,1,0] neg_lo:[0,0,1] neg_hi:[0,0,1]
	v_mul_f32_e32 v136, v139, v188
	v_pk_fma_f32 v[188:189], v[138:139], v[188:189], v[136:137] op_sel:[0,1,0] op_sel_hi:[1,0,0]
	v_pk_mul_f32 v[138:139], v[132:133], v[182:183]
	v_pk_fma_f32 v[132:133], v[132:133], v[182:183], v[194:195] op_sel_hi:[0,1,1]
	v_mul_f32_e32 v132, v135, v185
	v_pk_fma_f32 v[182:183], v[134:135], v[184:185], v[132:133] op_sel_hi:[1,1,0] neg_lo:[0,0,1] neg_hi:[0,0,1]
	v_mul_f32_e32 v132, v135, v184
	v_pk_fma_f32 v[184:185], v[134:135], v[184:185], v[132:133] op_sel:[0,1,0] op_sel_hi:[1,0,0]
	v_sub_f32_e32 v132, v138, v194
	v_sub_f32_e32 v136, v190, v192
	v_mov_b32_e32 v134, v182
	v_mov_b32_e32 v135, v184
	v_mov_b32_e32 v138, v186
	v_mov_b32_e32 v139, v188
.LBB0_429:
	s_or_b64 exec, exec, s[0:1]
	v_cvt_pk_bf16_f32 v136, v136, v137
	v_cvt_pk_bf16_f32 v137, v138, v139
	v_cvt_pk_bf16_f32 v138, v132, v133
	v_cvt_pk_bf16_f32 v139, v134, v135
	v_mov_b64_e32 v[132:133], s[68:69]
	v_mov_b32_e32 v134, v160
	v_mov_b32_e32 v135, v160
	v_mad_i64_i32 v[132:133], s[0:1], v178, s61, v[132:133]
	v_ashrrev_i32_e32 v159, 31, v158
	v_pk_mul_f32 v[130:131], v[130:131], v[134:135]
	v_pk_mul_f32 v[126:127], v[126:127], v[134:135]
	v_or_b32_e32 v134, 0x80, v158
	v_lshl_add_u64 v[132:133], v[158:159], 1, v[132:133]
	v_mul_hi_i32 v135, v134, s49
	global_store_dwordx4 v[132:133], v[136:139], off
	v_mov_b32_e32 v161, v160
	v_pk_mul_f32 v[128:129], v[128:129], v[160:161]
	v_lshrrev_b32_e32 v136, 31, v135
	v_lshrrev_b32_e32 v135, 5, v135
	v_add_u32_e32 v135, v135, v136
	v_mul_lo_u32 v135, v135, s59
	v_sub_u32_e32 v134, v134, v135
	v_cmp_lt_i32_e64 s[6:7], s60, v134
	v_add_u32_e32 v134, 0xffffff80, v134
	v_pk_mul_f32 v[124:125], v[124:125], v[160:161]
	v_lshrrev_b32_e32 v134, 1, v134
	v_add_u32_e32 v235, 0x20, v178
	v_lshlrev_b32_e32 v235, 5, v235
	v_and_b32_e32 v235, 0xffe0, v235
	v_add_u32_e32 v246, v235, v234
	v_lshl_add_u64 v[244:245], v[246:247], 3, s[54:55]
	global_load_dwordx4 v[200:203], v[244:245], off
	global_load_dwordx4 v[204:207], v[244:245], off offset:16
	s_and_saveexec_b64 s[0:1], s[6:7]
	s_cbranch_execz .LBB0_431
	s_waitcnt vmcnt(9)
	v_mov_b64_e32 v[136:137], v[212:213]
	v_mov_b64_e32 v[138:139], v[214:215]
	v_mov_b64_e32 v[182:183], v[208:209]
	v_mov_b64_e32 v[184:185], v[210:211]
	s_nop 0
	v_pk_mul_f32 v[188:189], v[124:125], v[136:137] op_sel:[1,1] op_sel_hi:[1,0]
	s_nop 0
	v_pk_mul_f32 v[186:187], v[128:129], v[182:183] op_sel:[1,1] op_sel_hi:[1,0]
	v_pk_mul_f32 v[160:161], v[128:129], v[182:183]
	v_pk_fma_f32 v[128:129], v[128:129], v[182:183], v[186:187] op_sel_hi:[0,1,1]
	v_mul_f32_e32 v128, v131, v185
	v_pk_fma_f32 v[182:183], v[130:131], v[184:185], v[128:129] op_sel_hi:[1,1,0] neg_lo:[0,0,1] neg_hi:[0,0,1]
	v_mul_f32_e32 v128, v131, v184
	v_pk_fma_f32 v[184:185], v[130:131], v[184:185], v[128:129] op_sel:[0,1,0] op_sel_hi:[1,0,0]
	v_pk_mul_f32 v[130:131], v[124:125], v[136:137]
	v_pk_fma_f32 v[124:125], v[124:125], v[136:137], v[188:189] op_sel_hi:[0,1,1]
	v_mul_f32_e32 v124, v127, v139
	v_pk_fma_f32 v[136:137], v[126:127], v[138:139], v[124:125] op_sel_hi:[1,1,0] neg_lo:[0,0,1] neg_hi:[0,0,1]
	v_mul_f32_e32 v124, v127, v138
	v_pk_fma_f32 v[138:139], v[126:127], v[138:139], v[124:125] op_sel:[0,1,0] op_sel_hi:[1,0,0]
	v_sub_f32_e32 v124, v130, v188
	v_sub_f32_e32 v128, v160, v186
	v_mov_b32_e32 v126, v136
	v_mov_b32_e32 v127, v138
	v_mov_b32_e32 v130, v182
	v_mov_b32_e32 v131, v184
.LBB0_431:
	s_or_b64 exec, exec, s[0:1]
	v_cvt_pk_bf16_f32 v128, v128, v129
	v_cvt_pk_bf16_f32 v129, v130, v131
	v_cvt_pk_bf16_f32 v130, v124, v125
	ds_bpermute_b32 v124, v177, v180 offset:64
	v_cvt_pk_bf16_f32 v131, v126, v127
	v_or_b32_e32 v127, 16, v178
	v_lshlrev_b32_e32 v125, 5, v127
	v_and_b32_e32 v126, 0xfbe0, v125
	s_waitcnt lgkmcnt(0)
	v_pk_mul_f32 v[122:123], v[122:123], v[124:125] op_sel_hi:[1,0]
	v_pk_mul_f32 v[120:121], v[120:121], v[124:125] op_sel_hi:[1,0]
	v_pk_mul_f32 v[118:119], v[118:119], v[124:125] op_sel_hi:[1,0]
	v_pk_mul_f32 v[116:117], v[116:117], v[124:125] op_sel_hi:[1,0]
	global_store_dwordx4 v[132:133], v[128:131], off offset:256
	v_add_u32_e32 v235, 0x30, v178
	v_lshlrev_b32_e32 v235, 5, v235
	v_and_b32_e32 v235, 0xffe0, v235
	v_add_u32_e32 v246, v235, v232
	v_lshl_add_u64 v[244:245], v[246:247], 3, s[54:55]
	global_load_dwordx4 v[208:211], v[244:245], off
	global_load_dwordx4 v[212:215], v[244:245], off offset:16
	s_and_saveexec_b64 s[0:1], s[4:5]
	s_cbranch_execz .LBB0_433
	s_waitcnt vmcnt(10)
	v_mov_b64_e32 v[128:129], v[220:221]
	v_mov_b64_e32 v[130:131], v[222:223]
	v_mov_b64_e32 v[136:137], v[216:217]
	v_mov_b64_e32 v[138:139], v[218:219]
	s_nop 0
	v_pk_mul_f32 v[182:183], v[116:117], v[128:129] op_sel:[1,1] op_sel_hi:[1,0]
	s_nop 0
	v_pk_mul_f32 v[160:161], v[120:121], v[136:137] op_sel:[1,1] op_sel_hi:[1,0]
	v_pk_mul_f32 v[132:133], v[120:121], v[136:137]
	v_pk_fma_f32 v[120:121], v[120:121], v[136:137], v[160:161] op_sel_hi:[0,1,1]
	v_mul_f32_e32 v120, v123, v139
	v_pk_fma_f32 v[136:137], v[122:123], v[138:139], v[120:121] op_sel_hi:[1,1,0] neg_lo:[0,0,1] neg_hi:[0,0,1]
	v_mul_f32_e32 v120, v123, v138
	v_pk_fma_f32 v[138:139], v[122:123], v[138:139], v[120:121] op_sel:[0,1,0] op_sel_hi:[1,0,0]
	v_pk_mul_f32 v[122:123], v[116:117], v[128:129]
	v_pk_fma_f32 v[116:117], v[116:117], v[128:129], v[182:183] op_sel_hi:[0,1,1]
	v_mul_f32_e32 v116, v119, v131
	v_pk_fma_f32 v[128:129], v[118:119], v[130:131], v[116:117] op_sel_hi:[1,1,0] neg_lo:[0,0,1] neg_hi:[0,0,1]
	v_mul_f32_e32 v116, v119, v130
	v_pk_fma_f32 v[130:131], v[118:119], v[130:131], v[116:117] op_sel:[0,1,0] op_sel_hi:[1,0,0]
	v_sub_f32_e32 v116, v122, v182
	v_sub_f32_e32 v120, v132, v160
	v_mov_b32_e32 v118, v128
	v_mov_b32_e32 v119, v130
	v_mov_b32_e32 v122, v136
	v_mov_b32_e32 v123, v138
.LBB0_433:
	s_or_b64 exec, exec, s[0:1]
	v_cvt_pk_bf16_f32 v120, v120, v121
	v_cvt_pk_bf16_f32 v121, v122, v123
	v_cvt_pk_bf16_f32 v122, v116, v117
	v_mov_b64_e32 v[116:117], s[68:69]
	v_mov_b32_e32 v125, v124
	v_cvt_pk_bf16_f32 v123, v118, v119
	v_mad_i64_i32 v[116:117], s[0:1], v127, s61, v[116:117]
	v_mov_b32_e32 v118, v124
	v_mov_b32_e32 v119, v124
	v_lshl_add_u64 v[116:117], v[158:159], 1, v[116:117]
	v_pk_mul_f32 v[102:103], v[102:103], v[118:119]
	v_pk_mul_f32 v[100:101], v[100:101], v[124:125]
	v_pk_mul_f32 v[98:99], v[98:99], v[118:119]
	v_pk_mul_f32 v[96:97], v[96:97], v[124:125]
	global_store_dwordx4 v[116:117], v[120:123], off
	v_add_u32_e32 v235, 0x30, v178
	v_lshlrev_b32_e32 v235, 5, v235
	v_and_b32_e32 v235, 0xffe0, v235
	v_add_u32_e32 v246, v235, v234
	v_lshl_add_u64 v[244:245], v[246:247], 3, s[54:55]
	global_load_dwordx4 v[216:219], v[244:245], off
	global_load_dwordx4 v[220:223], v[244:245], off offset:16
	s_and_saveexec_b64 s[0:1], s[6:7]
	s_cbranch_execz .LBB0_435
	s_waitcnt vmcnt(11)
	v_mov_b64_e32 v[118:119], v[228:229]
	v_mov_b64_e32 v[120:121], v[230:231]
	v_mov_b64_e32 v[122:123], v[224:225]
	v_mov_b64_e32 v[124:125], v[226:227]
	s_nop 0
	v_pk_mul_f32 v[130:131], v[96:97], v[118:119] op_sel:[1,1] op_sel_hi:[1,0]
	s_nop 0
	v_pk_mul_f32 v[128:129], v[100:101], v[122:123] op_sel:[1,1] op_sel_hi:[1,0]
	v_pk_mul_f32 v[126:127], v[100:101], v[122:123]
	v_pk_fma_f32 v[100:101], v[100:101], v[122:123], v[128:129] op_sel_hi:[0,1,1]
	v_mul_f32_e32 v100, v103, v125
	v_pk_fma_f32 v[122:123], v[102:103], v[124:125], v[100:101] op_sel_hi:[1,1,0] neg_lo:[0,0,1] neg_hi:[0,0,1]
	v_mul_f32_e32 v100, v103, v124
	v_pk_fma_f32 v[124:125], v[102:103], v[124:125], v[100:101] op_sel:[0,1,0] op_sel_hi:[1,0,0]
	v_pk_mul_f32 v[102:103], v[96:97], v[118:119]
	v_pk_fma_f32 v[96:97], v[96:97], v[118:119], v[130:131] op_sel_hi:[0,1,1]
	v_mul_f32_e32 v96, v99, v121
	v_pk_fma_f32 v[118:119], v[98:99], v[120:121], v[96:97] op_sel_hi:[1,1,0] neg_lo:[0,0,1] neg_hi:[0,0,1]
	v_mul_f32_e32 v96, v99, v120
	v_pk_fma_f32 v[120:121], v[98:99], v[120:121], v[96:97] op_sel:[0,1,0] op_sel_hi:[1,0,0]
	v_sub_f32_e32 v96, v102, v130
	v_sub_f32_e32 v100, v126, v128
	v_mov_b32_e32 v98, v118
	v_mov_b32_e32 v99, v120
	v_mov_b32_e32 v102, v122
	v_mov_b32_e32 v103, v124
.LBB0_435:
	s_or_b64 exec, exec, s[0:1]
	v_cvt_pk_bf16_f32 v100, v100, v101
	v_cvt_pk_bf16_f32 v101, v102, v103
	v_cvt_pk_bf16_f32 v102, v96, v97
	ds_bpermute_b32 v96, v177, v180 offset:128
	v_cvt_pk_bf16_f32 v103, v98, v99
	v_or_b32_e32 v99, 32, v178
	v_lshlrev_b32_e32 v97, 5, v99
	v_and_b32_e32 v98, 0xfde0, v97
	s_waitcnt lgkmcnt(0)
	v_pk_mul_f32 v[94:95], v[94:95], v[96:97] op_sel_hi:[1,0]
	v_pk_mul_f32 v[92:93], v[92:93], v[96:97] op_sel_hi:[1,0]
	v_pk_mul_f32 v[90:91], v[90:91], v[96:97] op_sel_hi:[1,0]
	v_pk_mul_f32 v[88:89], v[88:89], v[96:97] op_sel_hi:[1,0]
	global_store_dwordx4 v[116:117], v[100:103], off offset:256
	v_add_u32_e32 v235, 0x80, v178
	v_lshlrev_b32_e32 v235, 5, v235
	v_and_b32_e32 v235, 0xffe0, v235
	v_add_u32_e32 v246, v235, v232
	v_lshl_add_u64 v[244:245], v[246:247], 3, s[54:55]
	global_load_dwordx4 v[224:227], v[244:245], off
	global_load_dwordx4 v[228:231], v[244:245], off offset:16
	s_and_saveexec_b64 s[0:1], s[4:5]
	s_cbranch_execz .LBB0_437
	s_waitcnt vmcnt(12)
	v_mov_b64_e32 v[100:101], v[240:241]
	v_mov_b64_e32 v[102:103], v[242:243]
	v_mov_b64_e32 v[116:117], v[236:237]
	v_mov_b64_e32 v[118:119], v[238:239]
	s_nop 0
	v_pk_mul_f32 v[124:125], v[88:89], v[100:101] op_sel:[1,1] op_sel_hi:[1,0]
	s_nop 0
	v_pk_mul_f32 v[122:123], v[92:93], v[116:117] op_sel:[1,1] op_sel_hi:[1,0]
	v_pk_mul_f32 v[120:121], v[92:93], v[116:117]
	v_pk_fma_f32 v[92:93], v[92:93], v[116:117], v[122:123] op_sel_hi:[0,1,1]
	v_mul_f32_e32 v92, v95, v119
	v_pk_fma_f32 v[116:117], v[94:95], v[118:119], v[92:93] op_sel_hi:[1,1,0] neg_lo:[0,0,1] neg_hi:[0,0,1]
	v_mul_f32_e32 v92, v95, v118
	v_pk_fma_f32 v[118:119], v[94:95], v[118:119], v[92:93] op_sel:[0,1,0] op_sel_hi:[1,0,0]
	v_pk_mul_f32 v[94:95], v[88:89], v[100:101]
	v_pk_fma_f32 v[88:89], v[88:89], v[100:101], v[124:125] op_sel_hi:[0,1,1]
	v_mul_f32_e32 v88, v91, v103
	v_pk_fma_f32 v[100:101], v[90:91], v[102:103], v[88:89] op_sel_hi:[1,1,0] neg_lo:[0,0,1] neg_hi:[0,0,1]
	v_mul_f32_e32 v88, v91, v102
	v_pk_fma_f32 v[102:103], v[90:91], v[102:103], v[88:89] op_sel:[0,1,0] op_sel_hi:[1,0,0]
	v_sub_f32_e32 v88, v94, v124
	v_sub_f32_e32 v92, v120, v122
	v_mov_b32_e32 v90, v100
	v_mov_b32_e32 v91, v102
	v_mov_b32_e32 v94, v116
	v_mov_b32_e32 v95, v118
.LBB0_437:
	s_or_b64 exec, exec, s[0:1]
	v_cvt_pk_bf16_f32 v92, v92, v93
	v_cvt_pk_bf16_f32 v93, v94, v95
	v_cvt_pk_bf16_f32 v94, v88, v89
	v_mov_b64_e32 v[88:89], s[68:69]
	v_mov_b32_e32 v97, v96
	v_cvt_pk_bf16_f32 v95, v90, v91
	v_mad_i64_i32 v[88:89], s[0:1], v99, s61, v[88:89]
	v_mov_b32_e32 v90, v96
	v_mov_b32_e32 v91, v96
	v_lshl_add_u64 v[88:89], v[158:159], 1, v[88:89]
	v_pk_mul_f32 v[86:87], v[86:87], v[90:91]
	v_pk_mul_f32 v[84:85], v[84:85], v[96:97]
	v_pk_mul_f32 v[82:83], v[82:83], v[90:91]
	v_pk_mul_f32 v[80:81], v[80:81], v[96:97]
	global_store_dwordx4 v[88:89], v[92:95], off
	v_add_u32_e32 v235, 0x80, v178
	v_lshlrev_b32_e32 v235, 5, v235
	v_and_b32_e32 v235, 0xffe0, v235
	v_add_u32_e32 v246, v235, v234
	v_lshl_add_u64 v[244:245], v[246:247], 3, s[54:55]
	global_load_dwordx4 v[236:239], v[244:245], off
	global_load_dwordx4 v[240:243], v[244:245], off offset:16
	s_and_saveexec_b64 s[0:1], s[6:7]
	s_cbranch_execz .LBB0_439
	s_waitcnt vmcnt(12)
	v_mov_b64_e32 v[90:91], v[204:205]
	v_mov_b64_e32 v[92:93], v[206:207]
	v_mov_b64_e32 v[94:95], v[200:201]
	v_mov_b64_e32 v[96:97], v[202:203]
	s_nop 0
	v_pk_mul_f32 v[102:103], v[80:81], v[90:91] op_sel:[1,1] op_sel_hi:[1,0]
	s_nop 0
	v_pk_mul_f32 v[100:101], v[84:85], v[94:95] op_sel:[1,1] op_sel_hi:[1,0]
	v_pk_mul_f32 v[98:99], v[84:85], v[94:95]
	v_pk_fma_f32 v[84:85], v[84:85], v[94:95], v[100:101] op_sel_hi:[0,1,1]
	v_mul_f32_e32 v84, v87, v97
	v_pk_fma_f32 v[94:95], v[86:87], v[96:97], v[84:85] op_sel_hi:[1,1,0] neg_lo:[0,0,1] neg_hi:[0,0,1]
	v_mul_f32_e32 v84, v87, v96
	v_pk_fma_f32 v[96:97], v[86:87], v[96:97], v[84:85] op_sel:[0,1,0] op_sel_hi:[1,0,0]
	v_pk_mul_f32 v[86:87], v[80:81], v[90:91]
	v_pk_fma_f32 v[80:81], v[80:81], v[90:91], v[102:103] op_sel_hi:[0,1,1]
	v_mul_f32_e32 v80, v83, v93
	v_pk_fma_f32 v[90:91], v[82:83], v[92:93], v[80:81] op_sel_hi:[1,1,0] neg_lo:[0,0,1] neg_hi:[0,0,1]
	v_mul_f32_e32 v80, v83, v92
	v_pk_fma_f32 v[92:93], v[82:83], v[92:93], v[80:81] op_sel:[0,1,0] op_sel_hi:[1,0,0]
	v_sub_f32_e32 v80, v86, v102
	v_sub_f32_e32 v84, v98, v100
	v_mov_b32_e32 v82, v90
	v_mov_b32_e32 v83, v92
	v_mov_b32_e32 v86, v94
	v_mov_b32_e32 v87, v96
.LBB0_439:
	s_or_b64 exec, exec, s[0:1]
	v_cvt_pk_bf16_f32 v84, v84, v85
	v_cvt_pk_bf16_f32 v85, v86, v87
	v_cvt_pk_bf16_f32 v86, v80, v81
	ds_bpermute_b32 v80, v177, v180 offset:192
	v_cvt_pk_bf16_f32 v87, v82, v83
	v_or_b32_e32 v83, 48, v178
	v_lshlrev_b32_e32 v81, 5, v83
	v_and_b32_e32 v82, 0xffe0, v81
	s_waitcnt lgkmcnt(0)
	v_pk_mul_f32 v[78:79], v[78:79], v[80:81] op_sel_hi:[1,0]
	v_pk_mul_f32 v[76:77], v[76:77], v[80:81] op_sel_hi:[1,0]
	v_pk_mul_f32 v[74:75], v[74:75], v[80:81] op_sel_hi:[1,0]
	v_pk_mul_f32 v[72:73], v[72:73], v[80:81] op_sel_hi:[1,0]
	global_store_dwordx4 v[88:89], v[84:87], off offset:256
	v_add_u32_e32 v235, 0x90, v178
	v_lshlrev_b32_e32 v235, 5, v235
	v_and_b32_e32 v235, 0xffe0, v235
	v_add_u32_e32 v246, v235, v232
	v_lshl_add_u64 v[244:245], v[246:247], 3, s[54:55]
	global_load_dwordx4 v[200:203], v[244:245], off
	global_load_dwordx4 v[204:207], v[244:245], off offset:16
	s_and_saveexec_b64 s[0:1], s[4:5]
	s_cbranch_execz .LBB0_441
	s_waitcnt vmcnt(12)
	v_mov_b64_e32 v[84:85], v[212:213]
	v_mov_b64_e32 v[86:87], v[214:215]
	v_mov_b64_e32 v[88:89], v[208:209]
	v_mov_b64_e32 v[90:91], v[210:211]
	s_nop 0
	v_pk_mul_f32 v[96:97], v[72:73], v[84:85] op_sel:[1,1] op_sel_hi:[1,0]
	s_nop 0
	v_pk_mul_f32 v[94:95], v[76:77], v[88:89] op_sel:[1,1] op_sel_hi:[1,0]
	v_pk_mul_f32 v[92:93], v[76:77], v[88:89]
	v_pk_fma_f32 v[76:77], v[76:77], v[88:89], v[94:95] op_sel_hi:[0,1,1]
	v_mul_f32_e32 v76, v79, v91
	v_pk_fma_f32 v[88:89], v[78:79], v[90:91], v[76:77] op_sel_hi:[1,1,0] neg_lo:[0,0,1] neg_hi:[0,0,1]
	v_mul_f32_e32 v76, v79, v90
	v_pk_fma_f32 v[90:91], v[78:79], v[90:91], v[76:77] op_sel:[0,1,0] op_sel_hi:[1,0,0]
	v_pk_mul_f32 v[78:79], v[72:73], v[84:85]
	v_pk_fma_f32 v[72:73], v[72:73], v[84:85], v[96:97] op_sel_hi:[0,1,1]
	v_mul_f32_e32 v72, v75, v87
	v_pk_fma_f32 v[84:85], v[74:75], v[86:87], v[72:73] op_sel_hi:[1,1,0] neg_lo:[0,0,1] neg_hi:[0,0,1]
	v_mul_f32_e32 v72, v75, v86
	v_pk_fma_f32 v[86:87], v[74:75], v[86:87], v[72:73] op_sel:[0,1,0] op_sel_hi:[1,0,0]
	v_sub_f32_e32 v72, v78, v96
	v_sub_f32_e32 v76, v92, v94
	v_mov_b32_e32 v74, v84
	v_mov_b32_e32 v75, v86
	v_mov_b32_e32 v78, v88
	v_mov_b32_e32 v79, v90
.LBB0_441:
	s_or_b64 exec, exec, s[0:1]
	v_cvt_pk_bf16_f32 v76, v76, v77
	v_cvt_pk_bf16_f32 v77, v78, v79
	v_cvt_pk_bf16_f32 v78, v72, v73
	v_mov_b64_e32 v[72:73], s[68:69]
	v_mov_b32_e32 v81, v80
	v_cvt_pk_bf16_f32 v79, v74, v75
	v_mad_i64_i32 v[72:73], s[0:1], v83, s61, v[72:73]
	v_mov_b32_e32 v74, v80
	v_mov_b32_e32 v75, v80
	v_lshl_add_u64 v[72:73], v[158:159], 1, v[72:73]
	v_pk_mul_f32 v[70:71], v[70:71], v[74:75]
	v_pk_mul_f32 v[68:69], v[68:69], v[80:81]
	v_pk_mul_f32 v[66:67], v[66:67], v[74:75]
	v_pk_mul_f32 v[64:65], v[64:65], v[80:81]
	global_store_dwordx4 v[72:73], v[76:79], off
	v_add_u32_e32 v235, 0x90, v178
	v_lshlrev_b32_e32 v235, 5, v235
	v_and_b32_e32 v235, 0xffe0, v235
	v_add_u32_e32 v246, v235, v234
	v_lshl_add_u64 v[244:245], v[246:247], 3, s[54:55]
	global_load_dwordx4 v[208:211], v[244:245], off
	global_load_dwordx4 v[212:215], v[244:245], off offset:16
	s_and_saveexec_b64 s[0:1], s[6:7]
	s_cbranch_execz .LBB0_443
	s_waitcnt vmcnt(12)
	v_mov_b64_e32 v[74:75], v[220:221]
	v_mov_b64_e32 v[76:77], v[222:223]
	v_mov_b64_e32 v[78:79], v[216:217]
	v_mov_b64_e32 v[80:81], v[218:219]
	s_nop 0
	v_pk_mul_f32 v[86:87], v[64:65], v[74:75] op_sel:[1,1] op_sel_hi:[1,0]
	s_nop 0
	v_pk_mul_f32 v[84:85], v[68:69], v[78:79] op_sel:[1,1] op_sel_hi:[1,0]
	v_pk_mul_f32 v[82:83], v[68:69], v[78:79]
	v_pk_fma_f32 v[68:69], v[68:69], v[78:79], v[84:85] op_sel_hi:[0,1,1]
	v_mul_f32_e32 v68, v71, v81
	v_pk_fma_f32 v[78:79], v[70:71], v[80:81], v[68:69] op_sel_hi:[1,1,0] neg_lo:[0,0,1] neg_hi:[0,0,1]
	v_mul_f32_e32 v68, v71, v80
	v_pk_fma_f32 v[80:81], v[70:71], v[80:81], v[68:69] op_sel:[0,1,0] op_sel_hi:[1,0,0]
	v_pk_mul_f32 v[70:71], v[64:65], v[74:75]
	v_pk_fma_f32 v[64:65], v[64:65], v[74:75], v[86:87] op_sel_hi:[0,1,1]
	v_mul_f32_e32 v64, v67, v77
	v_pk_fma_f32 v[74:75], v[66:67], v[76:77], v[64:65] op_sel_hi:[1,1,0] neg_lo:[0,0,1] neg_hi:[0,0,1]
	v_mul_f32_e32 v64, v67, v76
	v_pk_fma_f32 v[76:77], v[66:67], v[76:77], v[64:65] op_sel:[0,1,0] op_sel_hi:[1,0,0]
	v_sub_f32_e32 v64, v70, v86
	v_sub_f32_e32 v68, v82, v84
	v_mov_b32_e32 v66, v74
	v_mov_b32_e32 v67, v76
	v_mov_b32_e32 v70, v78
	v_mov_b32_e32 v71, v80
.LBB0_443:
	s_or_b64 exec, exec, s[0:1]
	v_add_f32_e32 v74, v112, v113
	v_add_f32_e32 v75, v114, v115
	v_add_f32_e32 v74, v74, v75
	v_add_f32_e32 v75, v108, v109
	v_add_f32_e32 v76, v110, v111
	v_add_f32_e32 v75, v75, v76
	v_add_f32_e32 v74, v74, v75
	v_add_f32_e32 v75, v104, v105
	v_add_f32_e32 v76, v106, v107
	v_add_f32_e32 v75, v75, v76
	v_add_f32_e32 v74, v74, v75
	v_fmamk_f32 v74, v74, 0x3b2aaaab, v175
	v_mul_f32_e32 v75, 0x4f800000, v74
	v_cmp_gt_f32_e32 vcc, s57, v74
	v_cvt_pk_bf16_f32 v68, v68, v69
	v_cvt_pk_bf16_f32 v69, v70, v71
	v_cvt_pk_bf16_f32 v70, v64, v65
	v_cvt_pk_bf16_f32 v71, v66, v67
	v_add_u32_e32 v67, 0x80, v178
	s_nop 0
	v_cndmask_b32_e32 v74, v74, v75, vcc
	v_sqrt_f32_e32 v75, v74
	v_lshlrev_b32_e32 v65, 5, v67
	v_and_b32_e32 v66, 0xf9e0, v65
	global_store_dwordx4 v[72:73], v[68:71], off offset:256
	v_add_u32_e32 v76, -1, v75
	v_fma_f32 v77, -v76, v75, v74
	v_cmp_ge_f32_e64 s[0:1], 0, v77
	v_add_u32_e32 v77, 1, v75
	s_nop 0
	v_cndmask_b32_e64 v76, v75, v76, s[0:1]
	v_fma_f32 v75, -v77, v75, v74
	v_cmp_lt_f32_e64 s[0:1], 0, v75
	s_nop 1
	v_cndmask_b32_e64 v75, v76, v77, s[0:1]
	v_mul_f32_e32 v76, 0x37800000, v75
	v_cndmask_b32_e32 v75, v75, v76, vcc
	v_cmp_class_f32_e32 vcc, v74, v176
	s_nop 1
	v_cndmask_b32_e32 v74, v75, v74, vcc
	v_div_scale_f32 v75, s[0:1], v74, v74, s58
	v_rcp_f32_e32 v76, v75
	s_nop 0
	v_fma_f32 v77, -v75, v76, 1.0
	v_fmac_f32_e32 v76, v77, v76
	v_div_scale_f32 v77, vcc, s58, v74, s58
	v_mul_f32_e32 v78, v77, v76
	v_fma_f32 v79, -v75, v78, v77
	v_fmac_f32_e32 v78, v79, v76
	v_fma_f32 v75, -v75, v78, v77
	v_div_fmas_f32 v75, v75, v76, v78
	v_div_fixup_f32 v74, v75, v74, s58
	ds_bpermute_b32 v64, v177, v74
	s_waitcnt lgkmcnt(0)
	v_pk_mul_f32 v[62:63], v[62:63], v[64:65] op_sel_hi:[1,0]
	v_pk_mul_f32 v[60:61], v[60:61], v[64:65] op_sel_hi:[1,0]
	v_pk_mul_f32 v[58:59], v[58:59], v[64:65] op_sel_hi:[1,0]
	v_pk_mul_f32 v[56:57], v[56:57], v[64:65] op_sel_hi:[1,0]
	v_add_u32_e32 v235, 0xa0, v178
	v_lshlrev_b32_e32 v235, 5, v235
	v_and_b32_e32 v235, 0xffe0, v235
	v_add_u32_e32 v246, v235, v232
	v_lshl_add_u64 v[244:245], v[246:247], 3, s[54:55]
	global_load_dwordx4 v[216:219], v[244:245], off
	global_load_dwordx4 v[220:223], v[244:245], off offset:16
	s_and_saveexec_b64 s[0:1], s[4:5]
	s_cbranch_execz .LBB0_445
	s_waitcnt vmcnt(12)
	v_mov_b64_e32 v[68:69], v[228:229]
	v_mov_b64_e32 v[70:71], v[230:231]
	v_mov_b64_e32 v[76:77], v[224:225]
	v_mov_b64_e32 v[78:79], v[226:227]
	s_nop 0
	v_pk_mul_f32 v[82:83], v[56:57], v[68:69] op_sel:[1,1] op_sel_hi:[1,0]
	s_nop 0
	v_pk_mul_f32 v[80:81], v[60:61], v[76:77] op_sel:[1,1] op_sel_hi:[1,0]
	v_pk_mul_f32 v[72:73], v[60:61], v[76:77]
	v_pk_fma_f32 v[60:61], v[60:61], v[76:77], v[80:81] op_sel_hi:[0,1,1]
	v_mul_f32_e32 v60, v63, v79
	v_pk_fma_f32 v[76:77], v[62:63], v[78:79], v[60:61] op_sel_hi:[1,1,0] neg_lo:[0,0,1] neg_hi:[0,0,1]
	v_mul_f32_e32 v60, v63, v78
	v_pk_fma_f32 v[78:79], v[62:63], v[78:79], v[60:61] op_sel:[0,1,0] op_sel_hi:[1,0,0]
	v_pk_mul_f32 v[62:63], v[56:57], v[68:69]
	v_pk_fma_f32 v[56:57], v[56:57], v[68:69], v[82:83] op_sel_hi:[0,1,1]
	v_mul_f32_e32 v56, v59, v71
	v_pk_fma_f32 v[68:69], v[58:59], v[70:71], v[56:57] op_sel_hi:[1,1,0] neg_lo:[0,0,1] neg_hi:[0,0,1]
	v_mul_f32_e32 v56, v59, v70
	v_pk_fma_f32 v[70:71], v[58:59], v[70:71], v[56:57] op_sel:[0,1,0] op_sel_hi:[1,0,0]
	v_sub_f32_e32 v56, v62, v82
	v_sub_f32_e32 v60, v72, v80
	v_mov_b32_e32 v58, v68
	v_mov_b32_e32 v59, v70
	v_mov_b32_e32 v62, v76
	v_mov_b32_e32 v63, v78
.LBB0_445:
	s_or_b64 exec, exec, s[0:1]
	v_cvt_pk_bf16_f32 v60, v60, v61
	v_cvt_pk_bf16_f32 v61, v62, v63
	v_cvt_pk_bf16_f32 v62, v56, v57
	v_mov_b64_e32 v[56:57], s[68:69]
	v_mov_b32_e32 v65, v64
	v_cvt_pk_bf16_f32 v63, v58, v59
	v_mad_i64_i32 v[56:57], s[0:1], v67, s61, v[56:57]
	v_mov_b32_e32 v58, v64
	v_mov_b32_e32 v59, v64
	v_lshl_add_u64 v[56:57], v[158:159], 1, v[56:57]
	v_pk_mul_f32 v[54:55], v[54:55], v[58:59]
	v_pk_mul_f32 v[52:53], v[52:53], v[64:65]
	v_pk_mul_f32 v[50:51], v[50:51], v[58:59]
	v_pk_mul_f32 v[48:49], v[48:49], v[64:65]
	global_store_dwordx4 v[56:57], v[60:63], off
	v_add_u32_e32 v235, 0xa0, v178
	v_lshlrev_b32_e32 v235, 5, v235
	v_and_b32_e32 v235, 0xffe0, v235
	v_add_u32_e32 v246, v235, v234
	v_lshl_add_u64 v[244:245], v[246:247], 3, s[54:55]
	global_load_dwordx4 v[224:227], v[244:245], off
	global_load_dwordx4 v[228:231], v[244:245], off offset:16
	s_and_saveexec_b64 s[0:1], s[6:7]
	s_cbranch_execz .LBB0_447
	s_waitcnt vmcnt(12)
	v_mov_b64_e32 v[58:59], v[240:241]
	v_mov_b64_e32 v[60:61], v[242:243]
	v_mov_b64_e32 v[62:63], v[236:237]
	v_mov_b64_e32 v[64:65], v[238:239]
	s_nop 0
	v_pk_mul_f32 v[70:71], v[48:49], v[58:59] op_sel:[1,1] op_sel_hi:[1,0]
	s_nop 0
	v_pk_mul_f32 v[68:69], v[52:53], v[62:63] op_sel:[1,1] op_sel_hi:[1,0]
	v_pk_mul_f32 v[66:67], v[52:53], v[62:63]
	v_pk_fma_f32 v[52:53], v[52:53], v[62:63], v[68:69] op_sel_hi:[0,1,1]
	v_mul_f32_e32 v52, v55, v65
	v_pk_fma_f32 v[62:63], v[54:55], v[64:65], v[52:53] op_sel_hi:[1,1,0] neg_lo:[0,0,1] neg_hi:[0,0,1]
	v_mul_f32_e32 v52, v55, v64
	v_pk_fma_f32 v[64:65], v[54:55], v[64:65], v[52:53] op_sel:[0,1,0] op_sel_hi:[1,0,0]
	v_pk_mul_f32 v[54:55], v[48:49], v[58:59]
	v_pk_fma_f32 v[48:49], v[48:49], v[58:59], v[70:71] op_sel_hi:[0,1,1]
	v_mul_f32_e32 v48, v51, v61
	v_pk_fma_f32 v[58:59], v[50:51], v[60:61], v[48:49] op_sel_hi:[1,1,0] neg_lo:[0,0,1] neg_hi:[0,0,1]
	v_mul_f32_e32 v48, v51, v60
	v_pk_fma_f32 v[60:61], v[50:51], v[60:61], v[48:49] op_sel:[0,1,0] op_sel_hi:[1,0,0]
	v_sub_f32_e32 v48, v54, v70
	v_sub_f32_e32 v52, v66, v68
	v_mov_b32_e32 v50, v58
	v_mov_b32_e32 v51, v60
	v_mov_b32_e32 v54, v62
	v_mov_b32_e32 v55, v64
.LBB0_447:
	s_or_b64 exec, exec, s[0:1]
	v_or_b32_e32 v58, 64, v177
	v_cvt_pk_bf16_f32 v52, v52, v53
	v_cvt_pk_bf16_f32 v53, v54, v55
	v_cvt_pk_bf16_f32 v54, v48, v49
	ds_bpermute_b32 v48, v58, v74
	v_cvt_pk_bf16_f32 v55, v50, v51
	v_add_u32_e32 v51, 0x90, v178
	v_lshlrev_b32_e32 v49, 5, v51
	v_and_b32_e32 v50, 0xfbe0, v49
	s_waitcnt lgkmcnt(0)
	v_pk_mul_f32 v[46:47], v[46:47], v[48:49] op_sel_hi:[1,0]
	v_pk_mul_f32 v[44:45], v[44:45], v[48:49] op_sel_hi:[1,0]
	v_pk_mul_f32 v[42:43], v[42:43], v[48:49] op_sel_hi:[1,0]
	v_pk_mul_f32 v[40:41], v[40:41], v[48:49] op_sel_hi:[1,0]
	global_store_dwordx4 v[56:57], v[52:55], off offset:256
	v_add_u32_e32 v235, 0xb0, v178
	v_lshlrev_b32_e32 v235, 5, v235
	v_and_b32_e32 v235, 0xffe0, v235
	v_add_u32_e32 v246, v235, v232
	v_lshl_add_u64 v[244:245], v[246:247], 3, s[54:55]
	global_load_dwordx4 v[236:239], v[244:245], off
	global_load_dwordx4 v[240:243], v[244:245], off offset:16
	s_and_saveexec_b64 s[0:1], s[4:5]
	s_cbranch_execz .LBB0_449
	s_waitcnt vmcnt(12)
	v_mov_b64_e32 v[52:53], v[204:205]
	v_mov_b64_e32 v[54:55], v[206:207]
	v_mov_b64_e32 v[56:57], v[200:201]
	v_mov_b64_e32 v[58:59], v[202:203]
	s_nop 0
	v_pk_mul_f32 v[64:65], v[40:41], v[52:53] op_sel:[1,1] op_sel_hi:[1,0]
	s_nop 0
	v_pk_mul_f32 v[62:63], v[44:45], v[56:57] op_sel:[1,1] op_sel_hi:[1,0]
	v_pk_mul_f32 v[60:61], v[44:45], v[56:57]
	v_pk_fma_f32 v[44:45], v[44:45], v[56:57], v[62:63] op_sel_hi:[0,1,1]
	v_mul_f32_e32 v44, v47, v59
	v_pk_fma_f32 v[56:57], v[46:47], v[58:59], v[44:45] op_sel_hi:[1,1,0] neg_lo:[0,0,1] neg_hi:[0,0,1]
	v_mul_f32_e32 v44, v47, v58
	v_pk_fma_f32 v[58:59], v[46:47], v[58:59], v[44:45] op_sel:[0,1,0] op_sel_hi:[1,0,0]
	v_pk_mul_f32 v[46:47], v[40:41], v[52:53]
	v_pk_fma_f32 v[40:41], v[40:41], v[52:53], v[64:65] op_sel_hi:[0,1,1]
	v_mul_f32_e32 v40, v43, v55
	v_pk_fma_f32 v[52:53], v[42:43], v[54:55], v[40:41] op_sel_hi:[1,1,0] neg_lo:[0,0,1] neg_hi:[0,0,1]
	v_mul_f32_e32 v40, v43, v54
	v_pk_fma_f32 v[54:55], v[42:43], v[54:55], v[40:41] op_sel:[0,1,0] op_sel_hi:[1,0,0]
	v_sub_f32_e32 v40, v46, v64
	v_sub_f32_e32 v44, v60, v62
	v_mov_b32_e32 v42, v52
	v_mov_b32_e32 v43, v54
	v_mov_b32_e32 v46, v56
	v_mov_b32_e32 v47, v58
.LBB0_449:
	s_or_b64 exec, exec, s[0:1]
	v_cvt_pk_bf16_f32 v44, v44, v45
	v_cvt_pk_bf16_f32 v45, v46, v47
	v_cvt_pk_bf16_f32 v46, v40, v41
	v_mov_b64_e32 v[40:41], s[68:69]
	v_mov_b32_e32 v49, v48
	v_cvt_pk_bf16_f32 v47, v42, v43
	v_mad_i64_i32 v[40:41], s[0:1], v51, s61, v[40:41]
	v_mov_b32_e32 v42, v48
	v_mov_b32_e32 v43, v48
	v_lshl_add_u64 v[40:41], v[158:159], 1, v[40:41]
	v_pk_mul_f32 v[38:39], v[38:39], v[42:43]
	v_pk_mul_f32 v[36:37], v[36:37], v[48:49]
	v_pk_mul_f32 v[34:35], v[34:35], v[42:43]
	v_pk_mul_f32 v[32:33], v[32:33], v[48:49]
	global_store_dwordx4 v[40:41], v[44:47], off
	v_add_u32_e32 v235, 0xb0, v178
	v_lshlrev_b32_e32 v235, 5, v235
	v_and_b32_e32 v235, 0xffe0, v235
	v_add_u32_e32 v246, v235, v234
	v_lshl_add_u64 v[244:245], v[246:247], 3, s[54:55]
	global_load_dwordx4 v[200:203], v[244:245], off
	global_load_dwordx4 v[204:207], v[244:245], off offset:16
	s_and_saveexec_b64 s[0:1], s[6:7]
	s_cbranch_execz .LBB0_451
	s_waitcnt vmcnt(12)
	v_mov_b64_e32 v[42:43], v[212:213]
	v_mov_b64_e32 v[44:45], v[214:215]
	v_mov_b64_e32 v[46:47], v[208:209]
	v_mov_b64_e32 v[48:49], v[210:211]
	s_nop 0
	v_pk_mul_f32 v[54:55], v[32:33], v[42:43] op_sel:[1,1] op_sel_hi:[1,0]
	s_nop 0
	v_pk_mul_f32 v[52:53], v[36:37], v[46:47] op_sel:[1,1] op_sel_hi:[1,0]
	v_pk_mul_f32 v[50:51], v[36:37], v[46:47]
	v_pk_fma_f32 v[36:37], v[36:37], v[46:47], v[52:53] op_sel_hi:[0,1,1]
	v_mul_f32_e32 v36, v39, v49
	v_pk_fma_f32 v[46:47], v[38:39], v[48:49], v[36:37] op_sel_hi:[1,1,0] neg_lo:[0,0,1] neg_hi:[0,0,1]
	v_mul_f32_e32 v36, v39, v48
	v_pk_fma_f32 v[48:49], v[38:39], v[48:49], v[36:37] op_sel:[0,1,0] op_sel_hi:[1,0,0]
	v_pk_mul_f32 v[38:39], v[32:33], v[42:43]
	v_pk_fma_f32 v[32:33], v[32:33], v[42:43], v[54:55] op_sel_hi:[0,1,1]
	v_mul_f32_e32 v32, v35, v45
	v_pk_fma_f32 v[42:43], v[34:35], v[44:45], v[32:33] op_sel_hi:[1,1,0] neg_lo:[0,0,1] neg_hi:[0,0,1]
	v_mul_f32_e32 v32, v35, v44
	v_pk_fma_f32 v[44:45], v[34:35], v[44:45], v[32:33] op_sel:[0,1,0] op_sel_hi:[1,0,0]
	v_sub_f32_e32 v32, v38, v54
	v_sub_f32_e32 v36, v50, v52
	v_mov_b32_e32 v34, v42
	v_mov_b32_e32 v35, v44
	v_mov_b32_e32 v38, v46
	v_mov_b32_e32 v39, v48
.LBB0_451:
	s_or_b64 exec, exec, s[0:1]
	v_or_b32_e32 v42, 0x80, v177
	v_cvt_pk_bf16_f32 v36, v36, v37
	v_cvt_pk_bf16_f32 v37, v38, v39
	v_cvt_pk_bf16_f32 v38, v32, v33
	ds_bpermute_b32 v32, v42, v74
	v_cvt_pk_bf16_f32 v39, v34, v35
	v_add_u32_e32 v35, 0xa0, v178
	v_lshlrev_b32_e32 v33, 5, v35
	v_and_b32_e32 v34, 0xfde0, v33
	s_waitcnt lgkmcnt(0)
	v_pk_mul_f32 v[30:31], v[30:31], v[32:33] op_sel_hi:[1,0]
	v_pk_mul_f32 v[28:29], v[28:29], v[32:33] op_sel_hi:[1,0]
	v_pk_mul_f32 v[26:27], v[26:27], v[32:33] op_sel_hi:[1,0]
	v_pk_mul_f32 v[24:25], v[24:25], v[32:33] op_sel_hi:[1,0]
	global_store_dwordx4 v[40:41], v[36:39], off offset:256
	s_and_saveexec_b64 s[0:1], s[4:5]
	s_cbranch_execz .LBB0_453
	s_waitcnt vmcnt(10)
	v_mov_b64_e32 v[36:37], v[220:221]
	v_mov_b64_e32 v[38:39], v[222:223]
	v_mov_b64_e32 v[40:41], v[216:217]
	v_mov_b64_e32 v[42:43], v[218:219]
	s_nop 0
	v_pk_mul_f32 v[48:49], v[24:25], v[36:37] op_sel:[1,1] op_sel_hi:[1,0]
	s_nop 0
	v_pk_mul_f32 v[46:47], v[28:29], v[40:41] op_sel:[1,1] op_sel_hi:[1,0]
	v_pk_mul_f32 v[44:45], v[28:29], v[40:41]
	v_pk_fma_f32 v[28:29], v[28:29], v[40:41], v[46:47] op_sel_hi:[0,1,1]
	v_mul_f32_e32 v28, v31, v43
	v_pk_fma_f32 v[40:41], v[30:31], v[42:43], v[28:29] op_sel_hi:[1,1,0] neg_lo:[0,0,1] neg_hi:[0,0,1]
	v_mul_f32_e32 v28, v31, v42
	v_pk_fma_f32 v[42:43], v[30:31], v[42:43], v[28:29] op_sel:[0,1,0] op_sel_hi:[1,0,0]
	v_pk_mul_f32 v[30:31], v[24:25], v[36:37]
	v_pk_fma_f32 v[24:25], v[24:25], v[36:37], v[48:49] op_sel_hi:[0,1,1]
	v_mul_f32_e32 v24, v27, v39
	v_pk_fma_f32 v[36:37], v[26:27], v[38:39], v[24:25] op_sel_hi:[1,1,0] neg_lo:[0,0,1] neg_hi:[0,0,1]
	v_mul_f32_e32 v24, v27, v38
	v_pk_fma_f32 v[38:39], v[26:27], v[38:39], v[24:25] op_sel:[0,1,0] op_sel_hi:[1,0,0]
	v_sub_f32_e32 v24, v30, v48
	v_sub_f32_e32 v28, v44, v46
	v_mov_b32_e32 v26, v36
	v_mov_b32_e32 v27, v38
	v_mov_b32_e32 v30, v40
	v_mov_b32_e32 v31, v42
.LBB0_453:
	s_or_b64 exec, exec, s[0:1]
	v_cvt_pk_bf16_f32 v28, v28, v29
	v_cvt_pk_bf16_f32 v29, v30, v31
	v_cvt_pk_bf16_f32 v30, v24, v25
	v_mov_b64_e32 v[24:25], s[68:69]
	v_mov_b32_e32 v33, v32
	v_cvt_pk_bf16_f32 v31, v26, v27
	v_mad_i64_i32 v[24:25], s[0:1], v35, s61, v[24:25]
	v_mov_b32_e32 v26, v32
	v_mov_b32_e32 v27, v32
	v_lshl_add_u64 v[24:25], v[158:159], 1, v[24:25]
	v_pk_mul_f32 v[22:23], v[22:23], v[26:27]
	v_pk_mul_f32 v[20:21], v[20:21], v[32:33]
	v_pk_mul_f32 v[18:19], v[18:19], v[26:27]
	v_pk_mul_f32 v[16:17], v[16:17], v[32:33]
	global_store_dwordx4 v[24:25], v[28:31], off
	s_and_saveexec_b64 s[0:1], s[6:7]
	s_cbranch_execz .LBB0_455
	s_waitcnt vmcnt(8)
	v_mov_b64_e32 v[26:27], v[228:229]
	v_mov_b64_e32 v[28:29], v[230:231]
	v_mov_b64_e32 v[30:31], v[224:225]
	v_mov_b64_e32 v[32:33], v[226:227]
	s_nop 0
	v_pk_mul_f32 v[38:39], v[16:17], v[26:27] op_sel:[1,1] op_sel_hi:[1,0]
	s_nop 0
	v_pk_mul_f32 v[36:37], v[20:21], v[30:31] op_sel:[1,1] op_sel_hi:[1,0]
	v_pk_mul_f32 v[34:35], v[20:21], v[30:31]
	v_pk_fma_f32 v[20:21], v[20:21], v[30:31], v[36:37] op_sel_hi:[0,1,1]
	v_mul_f32_e32 v20, v23, v33
	v_pk_fma_f32 v[30:31], v[22:23], v[32:33], v[20:21] op_sel_hi:[1,1,0] neg_lo:[0,0,1] neg_hi:[0,0,1]
	v_mul_f32_e32 v20, v23, v32
	v_pk_fma_f32 v[32:33], v[22:23], v[32:33], v[20:21] op_sel:[0,1,0] op_sel_hi:[1,0,0]
	v_pk_mul_f32 v[22:23], v[16:17], v[26:27]
	v_pk_fma_f32 v[16:17], v[16:17], v[26:27], v[38:39] op_sel_hi:[0,1,1]
	v_mul_f32_e32 v16, v19, v29
	v_pk_fma_f32 v[26:27], v[18:19], v[28:29], v[16:17] op_sel_hi:[1,1,0] neg_lo:[0,0,1] neg_hi:[0,0,1]
	v_mul_f32_e32 v16, v19, v28
	v_pk_fma_f32 v[28:29], v[18:19], v[28:29], v[16:17] op_sel:[0,1,0] op_sel_hi:[1,0,0]
	v_sub_f32_e32 v16, v22, v38
	v_sub_f32_e32 v20, v34, v36
	v_mov_b32_e32 v18, v26
	v_mov_b32_e32 v19, v28
	v_mov_b32_e32 v22, v30
	v_mov_b32_e32 v23, v32
.LBB0_455:
	s_or_b64 exec, exec, s[0:1]
	v_or_b32_e32 v26, 0xc0, v177
	v_cvt_pk_bf16_f32 v20, v20, v21
	v_cvt_pk_bf16_f32 v21, v22, v23
	v_cvt_pk_bf16_f32 v22, v16, v17
	ds_bpermute_b32 v16, v26, v74
	v_cvt_pk_bf16_f32 v23, v18, v19
	v_add_u32_e32 v19, 0xb0, v178
	v_lshlrev_b32_e32 v17, 5, v19
	v_and_b32_e32 v18, 0xffe0, v17
	s_waitcnt lgkmcnt(0)
	v_pk_mul_f32 v[14:15], v[14:15], v[16:17] op_sel_hi:[1,0]
	v_pk_mul_f32 v[12:13], v[12:13], v[16:17] op_sel_hi:[1,0]
	v_pk_mul_f32 v[10:11], v[10:11], v[16:17] op_sel_hi:[1,0]
	v_pk_mul_f32 v[8:9], v[8:9], v[16:17] op_sel_hi:[1,0]
	global_store_dwordx4 v[24:25], v[20:23], off offset:256
	s_and_saveexec_b64 s[0:1], s[4:5]
	s_cbranch_execz .LBB0_457
	s_waitcnt vmcnt(6)
	v_mov_b64_e32 v[20:21], v[240:241]
	v_mov_b64_e32 v[22:23], v[242:243]
	v_mov_b64_e32 v[24:25], v[236:237]
	v_mov_b64_e32 v[26:27], v[238:239]
	s_nop 0
	v_pk_mul_f32 v[32:33], v[8:9], v[20:21] op_sel:[1,1] op_sel_hi:[1,0]
	s_nop 0
	v_pk_mul_f32 v[30:31], v[12:13], v[24:25] op_sel:[1,1] op_sel_hi:[1,0]
	v_pk_mul_f32 v[28:29], v[12:13], v[24:25]
	v_pk_fma_f32 v[12:13], v[12:13], v[24:25], v[30:31] op_sel_hi:[0,1,1]
	v_mul_f32_e32 v12, v15, v27
	v_pk_fma_f32 v[24:25], v[14:15], v[26:27], v[12:13] op_sel_hi:[1,1,0] neg_lo:[0,0,1] neg_hi:[0,0,1]
	v_mul_f32_e32 v12, v15, v26
	v_pk_fma_f32 v[26:27], v[14:15], v[26:27], v[12:13] op_sel:[0,1,0] op_sel_hi:[1,0,0]
	v_pk_mul_f32 v[14:15], v[8:9], v[20:21]
	v_pk_fma_f32 v[8:9], v[8:9], v[20:21], v[32:33] op_sel_hi:[0,1,1]
	v_mul_f32_e32 v8, v11, v23
	v_pk_fma_f32 v[20:21], v[10:11], v[22:23], v[8:9] op_sel_hi:[1,1,0] neg_lo:[0,0,1] neg_hi:[0,0,1]
	v_mul_f32_e32 v8, v11, v22
	v_pk_fma_f32 v[22:23], v[10:11], v[22:23], v[8:9] op_sel:[0,1,0] op_sel_hi:[1,0,0]
	v_sub_f32_e32 v8, v14, v32
	v_sub_f32_e32 v12, v28, v30
	v_mov_b32_e32 v10, v20
	v_mov_b32_e32 v11, v22
	v_mov_b32_e32 v14, v24
	v_mov_b32_e32 v15, v26
.LBB0_457:
	s_or_b64 exec, exec, s[0:1]
	v_cvt_pk_bf16_f32 v12, v12, v13
	v_cvt_pk_bf16_f32 v13, v14, v15
	v_cvt_pk_bf16_f32 v14, v8, v9
	v_mov_b64_e32 v[8:9], s[68:69]
	v_mov_b32_e32 v17, v16
	v_cvt_pk_bf16_f32 v15, v10, v11
	v_mad_i64_i32 v[8:9], s[0:1], v19, s61, v[8:9]
	v_mov_b32_e32 v10, v16
	v_mov_b32_e32 v11, v16
	v_lshl_add_u64 v[8:9], v[158:159], 1, v[8:9]
	v_pk_mul_f32 v[6:7], v[6:7], v[10:11]
	v_pk_mul_f32 v[4:5], v[4:5], v[16:17]
	v_pk_mul_f32 v[2:3], v[2:3], v[10:11]
	v_pk_mul_f32 v[0:1], v[0:1], v[16:17]
	global_store_dwordx4 v[8:9], v[12:15], off
	s_and_saveexec_b64 s[0:1], s[6:7]
	s_cbranch_execz .LBB0_459
	s_waitcnt vmcnt(4)
	v_mov_b64_e32 v[10:11], v[204:205]
	v_mov_b64_e32 v[12:13], v[206:207]
	v_mov_b64_e32 v[14:15], v[200:201]
	v_mov_b64_e32 v[16:17], v[202:203]
	s_nop 0
	v_pk_mul_f32 v[22:23], v[0:1], v[10:11] op_sel:[1,1] op_sel_hi:[1,0]
	s_nop 0
	v_pk_mul_f32 v[20:21], v[4:5], v[14:15] op_sel:[1,1] op_sel_hi:[1,0]
	v_pk_mul_f32 v[18:19], v[4:5], v[14:15]
	v_pk_fma_f32 v[4:5], v[4:5], v[14:15], v[20:21] op_sel_hi:[0,1,1]
	v_mul_f32_e32 v4, v7, v17
	v_pk_fma_f32 v[14:15], v[6:7], v[16:17], v[4:5] op_sel_hi:[1,1,0] neg_lo:[0,0,1] neg_hi:[0,0,1]
	v_mul_f32_e32 v4, v7, v16
	v_pk_fma_f32 v[16:17], v[6:7], v[16:17], v[4:5] op_sel:[0,1,0] op_sel_hi:[1,0,0]
	v_pk_mul_f32 v[6:7], v[0:1], v[10:11]
	v_pk_fma_f32 v[0:1], v[0:1], v[10:11], v[22:23] op_sel_hi:[0,1,1]
	v_mul_f32_e32 v0, v3, v13
	v_pk_fma_f32 v[10:11], v[2:3], v[12:13], v[0:1] op_sel_hi:[1,1,0] neg_lo:[0,0,1] neg_hi:[0,0,1]
	v_mul_f32_e32 v0, v3, v12
	v_pk_fma_f32 v[12:13], v[2:3], v[12:13], v[0:1] op_sel:[0,1,0] op_sel_hi:[1,0,0]
	v_sub_f32_e32 v0, v6, v22
	v_sub_f32_e32 v4, v18, v20
	v_mov_b32_e32 v2, v10
	v_mov_b32_e32 v3, v12
	v_mov_b32_e32 v6, v14
	v_mov_b32_e32 v7, v16
.LBB0_459:
	s_or_b64 exec, exec, s[0:1]
	s_waitcnt vmcnt(4)
	s_and_b64 vcc, exec, s[2:3]
	s_mov_b64 s[0:1], -1
	v_cvt_pk_bf16_f32 v4, v4, v5
	v_cvt_pk_bf16_f32 v5, v6, v7
	v_cvt_pk_bf16_f32 v6, v0, v1
	v_cvt_pk_bf16_f32 v7, v2, v3
	global_store_dwordx4 v[8:9], v[4:7], off offset:256
	s_cbranch_vccnz .LBB0_415
	s_andn2_b64 vcc, exec, s[8:9]
	s_cbranch_vccnz .LBB0_414
	s_barrier
	s_branch .LBB0_414
